# use the idle LDS pipe in the VALU-bound SGU-in epilogue: its 48 cross-lane hops go back to ds_bpermute (permlane swaps kept elsewhere); on top of v77
# baseline (speedup 1.0000x reference)
.LBB0_559:
	s_waitcnt lgkmcnt(0)
	v_pk_mul_f32 v[120:121], v[120:121], v[164:165] op_sel_hi:[1,0]
	s_bfe_u32 s8, s4, 0x20006
	v_mul_f32_e32 v145, v121, v121
	v_fmamk_f32 v145, v145, 0xbdd2d3e7, v152
	v_mul_f32_e32 v145, v121, v145
	s_lshl_b32 s4, s95, 8
	s_lshl_b32 s5, s8, 5
	v_pk_mul_f32 v[126:127], v[126:127], v[164:165] op_sel_hi:[1,0]
	v_pk_mul_f32 v[122:123], v[122:123], v[164:165] op_sel_hi:[1,0]
	s_or_b32 s4, s5, s4
	v_exp_f32_e32 v145, v145
	v_mul_f32_e32 v147, v126, v126
	v_mul_f32_e32 v148, v122, v122
	v_lshl_or_b32 v160, v162, 3, s4
	v_lshlrev_b64 v[142:143], 12, v[158:159]
	v_fmamk_f32 v147, v147, 0xbdd2d3e7, v152
	v_fmamk_f32 v148, v148, 0xbdd2d3e7, v152
	v_ashrrev_i32_e32 v161, 31, v160
	v_lshl_add_u64 v[142:143], s[70:71], 0, v[142:143]
	v_mul_f32_e32 v147, v126, v147
	v_mul_f32_e32 v148, v122, v148
	v_cmp_eq_u32_e32 vcc, 0, v162
	v_lshl_add_u64 v[162:163], v[160:161], 1, v[142:143]
	v_pk_mul_f32 v[124:125], v[124:125], v[164:165] op_sel_hi:[1,0]
	v_mul_f32_e32 v143, v120, v120
	v_mul_f32_e32 v142, v124, v124
	v_fmamk_f32 v143, v143, 0xbdd2d3e7, v152
	v_add_f32_e32 v145, 1.0, v145
	v_fmamk_f32 v142, v142, 0xbdd2d3e7, v152
	v_mul_f32_e32 v143, v120, v143
	v_mul_f32_e32 v144, v125, v125
	v_rcp_f32_e32 v145, v145
	v_exp_f32_e32 v147, v147
	v_exp_f32_e32 v148, v148
	v_mul_f32_e32 v142, v124, v142
	v_fmamk_f32 v144, v144, 0xbdd2d3e7, v152
	v_mul_f32_e32 v144, v125, v144
	v_exp_f32_e32 v143, v143
	v_mul_f32_e32 v149, v123, v123
	v_exp_f32_e32 v142, v142
	v_mul_f32_e32 v145, v121, v145
	v_add_f32_e32 v121, 1.0, v147
	v_add_f32_e32 v147, 1.0, v148
	v_mul_f32_e32 v148, v127, v127
	v_fmamk_f32 v149, v149, 0xbdd2d3e7, v152
	v_exp_f32_e32 v144, v144
	v_fmamk_f32 v148, v148, 0xbdd2d3e7, v152
	v_mul_f32_e32 v149, v123, v149
	v_mul_f32_e32 v148, v127, v148
	v_add_f32_e32 v143, 1.0, v143
	v_add_f32_e32 v142, 1.0, v142
	v_rcp_f32_e32 v143, v143
	v_exp_f32_e32 v149, v149
	v_rcp_f32_e32 v142, v142
	v_add_f32_e32 v144, 1.0, v144
	v_exp_f32_e32 v148, v148
	v_rcp_f32_e32 v144, v144
	v_rcp_f32_e32 v147, v147
	v_rcp_f32_e32 v121, v121
	v_mul_f32_e32 v143, v120, v143
	v_add_f32_e32 v149, 1.0, v149
	v_mul_f32_e32 v146, v124, v142
	v_add_f32_e32 v148, 1.0, v148
	v_rcp_f32_e32 v149, v149
	v_fma_f32 v124, v124, v142, v143
	v_mul_f32_e32 v120, v125, v144
	v_rcp_f32_e32 v148, v148
	v_mul_f32_e32 v147, v122, v147
	v_add_f32_e32 v124, 0, v124
	v_fma_f32 v125, v125, v144, v145
	v_mul_f32_e32 v150, v126, v121
	v_mul_f32_e32 v142, v143, v143
	v_add_f32_e32 v124, v125, v124
	v_mul_f32_e32 v125, v145, v145
	v_fma_f32 v121, v126, v121, v147
	v_fmac_f32_e32 v142, v146, v146
	v_fmac_f32_e32 v125, v120, v120
	v_add_f32_e32 v121, v121, v124
	v_mul_f32_e32 v124, v147, v147
	v_mul_f32_e32 v123, v123, v149
	v_add_f32_e32 v125, v142, v125
	v_fmac_f32_e32 v124, v150, v150
	v_add_f32_e32 v124, v124, v125
	v_fma_f32 v125, v127, v148, v123
	v_mul_f32_e32 v122, v127, v148
	v_add_f32_e32 v125, v125, v121
	v_mul_f32_e32 v121, v123, v123
	v_fmac_f32_e32 v121, v122, v122
	v_add_f32_e32 v124, v121, v124
	v_cvt_pk_bf16_f32 v120, v146, v120
	v_cvt_pk_bf16_f32 v121, v150, v122
	v_cvt_pk_bf16_f32 v122, v143, v145
	v_cvt_pk_bf16_f32 v123, v147, v123
	v_pk_mul_f32 v[112:113], v[112:113], v[164:165] op_sel_hi:[1,0]
	global_store_dwordx4 v[162:163], v[120:123], off nt
	v_pk_mul_f32 v[118:119], v[118:119], v[164:165] op_sel_hi:[1,0]
	v_pk_mul_f32 v[114:115], v[114:115], v[164:165] op_sel_hi:[1,0]
	v_mul_f32_e32 v123, v113, v113
	v_fmamk_f32 v123, v123, 0xbdd2d3e7, v152
	v_mul_f32_e32 v123, v113, v123
	v_exp_f32_e32 v123, v123
	v_mul_f32_e32 v127, v118, v118
	v_mul_f32_e32 v142, v114, v114
	v_fmamk_f32 v127, v127, 0xbdd2d3e7, v152
	v_fmamk_f32 v142, v142, 0xbdd2d3e7, v152
	v_mul_f32_e32 v127, v118, v127
	v_mul_f32_e32 v142, v114, v142
	v_pk_mul_f32 v[116:117], v[116:117], v[164:165] op_sel_hi:[1,0]
	v_mul_f32_e32 v121, v112, v112
	v_mul_f32_e32 v120, v116, v116
	v_fmamk_f32 v121, v121, 0xbdd2d3e7, v152
	v_add_f32_e32 v123, 1.0, v123
	v_fmamk_f32 v120, v120, 0xbdd2d3e7, v152
	v_mul_f32_e32 v121, v112, v121
	v_mul_f32_e32 v122, v117, v117
	v_rcp_f32_e32 v123, v123
	v_exp_f32_e32 v127, v127
	v_exp_f32_e32 v142, v142
	v_mul_f32_e32 v120, v116, v120
	v_fmamk_f32 v122, v122, 0xbdd2d3e7, v152
	v_mul_f32_e32 v122, v117, v122
	v_exp_f32_e32 v121, v121
	v_mul_f32_e32 v143, v115, v115
	v_exp_f32_e32 v120, v120
	v_mul_f32_e32 v113, v113, v123
	v_add_f32_e32 v123, 1.0, v127
	v_add_f32_e32 v127, 1.0, v142
	v_mul_f32_e32 v142, v119, v119
	v_fmamk_f32 v143, v143, 0xbdd2d3e7, v152
	v_exp_f32_e32 v122, v122
	v_fmamk_f32 v142, v142, 0xbdd2d3e7, v152
	v_mul_f32_e32 v143, v115, v143
	v_mul_f32_e32 v142, v119, v142
	v_add_f32_e32 v121, 1.0, v121
	v_add_f32_e32 v120, 1.0, v120
	v_rcp_f32_e32 v121, v121
	v_exp_f32_e32 v143, v143
	v_rcp_f32_e32 v120, v120
	v_add_f32_e32 v122, 1.0, v122
	v_exp_f32_e32 v142, v142
	v_rcp_f32_e32 v122, v122
	v_rcp_f32_e32 v127, v127
	v_rcp_f32_e32 v123, v123
	v_mul_f32_e32 v112, v112, v121
	v_add_f32_e32 v143, 1.0, v143
	v_mul_f32_e32 v126, v116, v120
	v_add_f32_e32 v142, 1.0, v142
	v_rcp_f32_e32 v143, v143
	v_fma_f32 v116, v116, v120, v112
	v_mul_f32_e32 v121, v117, v122
	v_rcp_f32_e32 v142, v142
	v_mul_f32_e32 v114, v114, v127
	v_add_f32_e32 v116, v116, v125
	v_mul_f32_e32 v120, v112, v112
	v_fma_f32 v117, v117, v122, v113
	v_mul_f32_e32 v144, v118, v123
	v_fmac_f32_e32 v120, v126, v126
	v_add_f32_e32 v116, v117, v116
	v_mul_f32_e32 v117, v113, v113
	v_fma_f32 v118, v118, v123, v114
	v_add_f32_e32 v120, v120, v124
	v_fmac_f32_e32 v117, v121, v121
	v_add_f32_e32 v116, v118, v116
	v_mul_f32_e32 v118, v114, v114
	v_mul_f32_e32 v115, v115, v143
	v_add_f32_e32 v117, v117, v120
	v_fmac_f32_e32 v118, v144, v144
	v_add_f32_e32 v117, v118, v117
	v_fma_f32 v118, v119, v142, v115
	v_mul_f32_e32 v127, v119, v142
	v_add_f32_e32 v120, v118, v116
	v_mul_f32_e32 v116, v115, v115
	v_fmac_f32_e32 v116, v127, v127
	v_add_f32_e32 v122, v116, v117
	v_cvt_pk_bf16_f32 v116, v126, v121
	ds_bpermute_b32 v121, v168, v120
	ds_bpermute_b32 v123, v168, v122
	v_cvt_pk_bf16_f32 v117, v144, v127
	v_cvt_pk_bf16_f32 v118, v112, v113
	v_cvt_pk_bf16_f32 v119, v114, v115
	s_waitcnt lgkmcnt(0)
	v_add_f32_e32 v112, v120, v121
	v_add_f32_e32 v114, v122, v123
	ds_bpermute_b32 v113, v167, v112
	ds_bpermute_b32 v115, v167, v114
	s_cmp_gt_i32 s95, 3
	s_cselect_b64 s[4:5], -1, 0
	s_and_b64 s[58:59], s[4:5], vcc
	global_store_dwordx4 v[162:163], v[116:119], off offset:256 nt
	s_and_saveexec_b64 s[6:7], s[58:59]
	s_cbranch_execz .LBB0_561
	s_waitcnt lgkmcnt(0)
	v_add_f32_e32 v114, v114, v115
	v_add_f32_e32 v115, v112, v113
	s_lshl_b32 s4, s95, 2
	v_lshlrev_b64 v[112:113], 7, v[158:159]
	s_add_i32 s38, s4, -16
	v_lshl_add_u64 v[112:113], s[72:73], 0, v[112:113]
	v_lshl_add_u64 v[112:113], s[38:39], 2, v[112:113]
	s_lshl_b32 s38, s8, 2
	v_lshl_add_u64 v[112:113], v[112:113], 0, s[38:39]
	global_store_dword v[112:113], v115, off
	global_store_dword v[112:113], v114, off offset:64

.LBB0_565:
	s_waitcnt lgkmcnt(0)
	v_pk_mul_f32 v[108:109], v[108:109], v[116:117] op_sel_hi:[1,0]
	v_lshlrev_b64 v[114:115], 12, v[112:113]
	v_mul_f32_e32 v117, v108, v108
	v_fmamk_f32 v117, v117, 0xbdd2d3e7, v152
	v_mul_f32_e32 v117, v108, v117
	v_exp_f32_e32 v117, v117
	v_mul_f32_e32 v119, v109, v109
	v_fmamk_f32 v119, v119, 0xbdd2d3e7, v152
	v_mul_f32_e32 v119, v109, v119
	v_pk_mul_f32 v[104:105], v[104:105], v[116:117] op_sel_hi:[1,0]
	v_pk_mul_f32 v[110:111], v[110:111], v[116:117] op_sel_hi:[1,0]
	v_mul_f32_e32 v120, v105, v105
	v_fmamk_f32 v120, v120, 0xbdd2d3e7, v152
	v_mul_f32_e32 v120, v105, v120
	v_pk_mul_f32 v[106:107], v[106:107], v[116:117] op_sel_hi:[1,0]
	v_exp_f32_e32 v120, v120
	v_mul_f32_e32 v122, v110, v110
	v_mul_f32_e32 v123, v106, v106
	v_fmamk_f32 v122, v122, 0xbdd2d3e7, v152
	v_fmamk_f32 v123, v123, 0xbdd2d3e7, v152
	v_mul_f32_e32 v118, v104, v104
	v_mul_f32_e32 v122, v110, v122
	v_mul_f32_e32 v123, v106, v123
	v_fmamk_f32 v118, v118, 0xbdd2d3e7, v152
	v_mul_f32_e32 v118, v104, v118
	v_add_f32_e32 v120, 1.0, v120
	v_rcp_f32_e32 v120, v120
	v_exp_f32_e32 v122, v122
	v_exp_f32_e32 v123, v123
	v_exp_f32_e32 v118, v118
	v_mul_f32_e32 v124, v107, v107
	v_exp_f32_e32 v119, v119
	v_mul_f32_e32 v120, v105, v120
	v_add_f32_e32 v105, 1.0, v122
	v_add_f32_e32 v122, 1.0, v123
	v_mul_f32_e32 v123, v111, v111
	v_fmamk_f32 v124, v124, 0xbdd2d3e7, v152
	v_fmamk_f32 v123, v123, 0xbdd2d3e7, v152
	v_mul_f32_e32 v124, v107, v124
	v_add_f32_e32 v118, 1.0, v118
	v_mul_f32_e32 v123, v111, v123
	v_add_f32_e32 v117, 1.0, v117
	v_rcp_f32_e32 v118, v118
	v_rcp_f32_e32 v117, v117
	v_add_f32_e32 v119, 1.0, v119
	v_exp_f32_e32 v124, v124
	v_rcp_f32_e32 v119, v119
	v_exp_f32_e32 v123, v123
	v_rcp_f32_e32 v122, v122
	v_mul_f32_e32 v118, v104, v118
	v_rcp_f32_e32 v105, v105
	v_mul_f32_e32 v121, v108, v117
	v_add_f32_e32 v124, 1.0, v124
	v_fma_f32 v108, v108, v117, v118
	v_mul_f32_e32 v104, v109, v119
	v_add_f32_e32 v123, 1.0, v123
	v_rcp_f32_e32 v124, v124
	v_add_f32_e32 v108, 0, v108
	v_mul_f32_e32 v117, v118, v118
	v_fma_f32 v109, v109, v119, v120
	v_rcp_f32_e32 v123, v123
	v_mul_f32_e32 v122, v106, v122
	v_fmac_f32_e32 v117, v121, v121
	v_add_f32_e32 v108, v109, v108
	v_mul_f32_e32 v109, v120, v120
	v_mul_f32_e32 v125, v110, v105
	v_fmac_f32_e32 v109, v104, v104
	v_fma_f32 v105, v110, v105, v122
	v_pk_mul_f32 v[96:97], v[96:97], v[116:117] op_sel_hi:[1,0]
	v_add_f32_e32 v109, v117, v109
	v_add_f32_e32 v105, v105, v108
	v_mul_f32_e32 v108, v122, v122
	v_pk_mul_f32 v[100:101], v[100:101], v[116:117] op_sel_hi:[1,0]
	v_pk_mul_f32 v[102:103], v[102:103], v[116:117] op_sel_hi:[1,0]
	v_pk_mul_f32 v[98:99], v[98:99], v[116:117] op_sel_hi:[1,0]
	v_mul_f32_e32 v117, v97, v97
	v_mul_f32_e32 v107, v107, v124
	v_fmac_f32_e32 v108, v125, v125
	v_fmamk_f32 v117, v117, 0xbdd2d3e7, v152
	v_add_f32_e32 v108, v108, v109
	v_fma_f32 v109, v111, v123, v107
	v_mul_f32_e32 v117, v97, v117
	v_mul_f32_e32 v106, v111, v123
	v_add_f32_e32 v109, v109, v105
	v_mul_f32_e32 v105, v107, v107
	v_fmac_f32_e32 v105, v106, v106
	v_add_f32_e32 v108, v105, v108
	v_cvt_pk_bf16_f32 v104, v121, v104
	v_cvt_pk_bf16_f32 v105, v125, v106
	v_cvt_pk_bf16_f32 v106, v118, v120
	v_exp_f32_e32 v117, v117
	v_mul_f32_e32 v119, v102, v102
	v_mul_f32_e32 v120, v98, v98
	v_fmamk_f32 v119, v119, 0xbdd2d3e7, v152
	v_fmamk_f32 v120, v120, 0xbdd2d3e7, v152
	v_mul_f32_e32 v119, v102, v119
	v_mul_f32_e32 v120, v98, v120
	v_mul_f32_e32 v111, v96, v96
	v_mul_f32_e32 v110, v100, v100
	v_fmamk_f32 v111, v111, 0xbdd2d3e7, v152
	v_add_f32_e32 v117, 1.0, v117
	v_fmamk_f32 v110, v110, 0xbdd2d3e7, v152
	v_mul_f32_e32 v111, v96, v111
	v_mul_f32_e32 v116, v101, v101
	v_rcp_f32_e32 v117, v117
	v_exp_f32_e32 v119, v119
	v_exp_f32_e32 v120, v120
	v_mul_f32_e32 v121, v99, v99
	v_mul_f32_e32 v110, v100, v110
	v_fmamk_f32 v116, v116, 0xbdd2d3e7, v152
	v_fmamk_f32 v121, v121, 0xbdd2d3e7, v152
	v_mul_f32_e32 v116, v101, v116
	v_mul_f32_e32 v121, v99, v121
	v_exp_f32_e32 v111, v111
	v_exp_f32_e32 v110, v110
	v_mul_f32_e32 v117, v97, v117
	v_add_f32_e32 v97, 1.0, v119
	v_add_f32_e32 v119, 1.0, v120
	v_mul_f32_e32 v120, v103, v103
	v_exp_f32_e32 v116, v116
	v_fmamk_f32 v120, v120, 0xbdd2d3e7, v152
	v_exp_f32_e32 v121, v121
	v_mul_f32_e32 v120, v103, v120
	v_add_f32_e32 v111, 1.0, v111
	v_add_f32_e32 v110, 1.0, v110
	v_rcp_f32_e32 v111, v111
	v_rcp_f32_e32 v110, v110
	v_add_f32_e32 v116, 1.0, v116
	v_exp_f32_e32 v120, v120
	v_rcp_f32_e32 v119, v119
	v_add_f32_e32 v121, 1.0, v121
	v_rcp_f32_e32 v116, v116
	v_rcp_f32_e32 v121, v121
	v_rcp_f32_e32 v97, v97
	v_mul_f32_e32 v111, v96, v111
	v_add_f32_e32 v120, 1.0, v120
	v_mul_f32_e32 v119, v98, v119
	v_fma_f32 v98, v100, v110, v111
	v_mul_f32_e32 v118, v100, v110
	v_rcp_f32_e32 v120, v120
	v_mul_f32_e32 v121, v99, v121
	v_add_f32_e32 v98, v98, v109
	v_mul_f32_e32 v99, v111, v111
	v_fma_f32 v100, v101, v116, v117
	v_cvt_pk_bf16_f32 v107, v122, v107
	v_mul_f32_e32 v96, v101, v116
	v_mul_f32_e32 v122, v102, v97
	v_fmac_f32_e32 v99, v118, v118
	v_add_f32_e32 v98, v100, v98
	v_mul_f32_e32 v100, v117, v117
	v_fma_f32 v97, v102, v97, v119
	v_add_f32_e32 v99, v99, v108
	v_fmac_f32_e32 v100, v96, v96
	v_add_f32_e32 v97, v97, v98
	v_mul_f32_e32 v98, v119, v119
	v_add_f32_e32 v99, v100, v99
	v_fmac_f32_e32 v98, v122, v122
	v_add_f32_e32 v98, v98, v99
	v_fma_f32 v99, v103, v120, v121
	v_mul_f32_e32 v123, v103, v120
	v_add_f32_e32 v97, v99, v97
	v_mul_f32_e32 v99, v121, v121
	v_fmac_f32_e32 v99, v123, v123
	v_add_f32_e32 v98, v99, v98
	ds_bpermute_b32 v101, v168, v97
	ds_bpermute_b32 v99, v168, v98
	v_lshl_add_u64 v[114:115], s[70:71], 0, v[114:115]
	v_lshl_add_u64 v[114:115], v[160:161], 1, v[114:115]
	global_store_dwordx4 v[114:115], v[104:107], off nt
	v_cvt_pk_bf16_f32 v100, v118, v96
	s_waitcnt lgkmcnt(0)
	v_add_f32_e32 v96, v97, v101
	v_add_f32_e32 v98, v98, v99
	ds_bpermute_b32 v97, v167, v96
	ds_bpermute_b32 v99, v167, v98
	v_cvt_pk_bf16_f32 v101, v122, v123
	v_cvt_pk_bf16_f32 v102, v111, v117
	v_cvt_pk_bf16_f32 v103, v119, v121
	global_store_dwordx4 v[114:115], v[100:103], off offset:256 nt
	s_and_saveexec_b64 s[6:7], s[58:59]
	s_cbranch_execz .LBB0_567
	s_waitcnt lgkmcnt(0)
	v_add_f32_e32 v98, v98, v99
	v_add_f32_e32 v99, v96, v97
	s_lshl_b32 s4, s95, 2
	v_lshlrev_b64 v[96:97], 7, v[112:113]
	s_add_i32 s38, s4, -16
	v_lshl_add_u64 v[96:97], s[72:73], 0, v[96:97]
	v_lshl_add_u64 v[96:97], s[38:39], 2, v[96:97]
	s_lshl_b32 s38, s8, 2
	v_lshl_add_u64 v[96:97], v[96:97], 0, s[38:39]
	global_store_dword v[96:97], v99, off
	global_store_dword v[96:97], v98, off offset:64

.LBB0_571:
	s_waitcnt lgkmcnt(0)
	v_pk_mul_f32 v[92:93], v[92:93], v[100:101] op_sel_hi:[1,0]
	v_lshlrev_b64 v[98:99], 12, v[96:97]
	v_mul_f32_e32 v101, v92, v92
	v_fmamk_f32 v101, v101, 0xbdd2d3e7, v152
	v_mul_f32_e32 v101, v92, v101
	v_exp_f32_e32 v101, v101
	v_mul_f32_e32 v103, v93, v93
	v_fmamk_f32 v103, v103, 0xbdd2d3e7, v152
	v_mul_f32_e32 v103, v93, v103
	v_pk_mul_f32 v[88:89], v[88:89], v[100:101] op_sel_hi:[1,0]
	v_pk_mul_f32 v[94:95], v[94:95], v[100:101] op_sel_hi:[1,0]
	v_mul_f32_e32 v104, v89, v89
	v_fmamk_f32 v104, v104, 0xbdd2d3e7, v152
	v_mul_f32_e32 v104, v89, v104
	v_pk_mul_f32 v[90:91], v[90:91], v[100:101] op_sel_hi:[1,0]
	v_exp_f32_e32 v104, v104
	v_mul_f32_e32 v106, v94, v94
	v_mul_f32_e32 v107, v90, v90
	v_fmamk_f32 v106, v106, 0xbdd2d3e7, v152
	v_fmamk_f32 v107, v107, 0xbdd2d3e7, v152
	v_mul_f32_e32 v102, v88, v88
	v_mul_f32_e32 v106, v94, v106
	v_mul_f32_e32 v107, v90, v107
	v_fmamk_f32 v102, v102, 0xbdd2d3e7, v152
	v_mul_f32_e32 v102, v88, v102
	v_add_f32_e32 v104, 1.0, v104
	v_rcp_f32_e32 v104, v104
	v_exp_f32_e32 v106, v106
	v_exp_f32_e32 v107, v107
	v_exp_f32_e32 v102, v102
	v_mul_f32_e32 v108, v91, v91
	v_exp_f32_e32 v103, v103
	v_mul_f32_e32 v104, v89, v104
	v_add_f32_e32 v89, 1.0, v106
	v_add_f32_e32 v106, 1.0, v107
	v_mul_f32_e32 v107, v95, v95
	v_fmamk_f32 v108, v108, 0xbdd2d3e7, v152
	v_fmamk_f32 v107, v107, 0xbdd2d3e7, v152
	v_mul_f32_e32 v108, v91, v108
	v_add_f32_e32 v102, 1.0, v102
	v_mul_f32_e32 v107, v95, v107
	v_add_f32_e32 v101, 1.0, v101
	v_rcp_f32_e32 v102, v102
	v_rcp_f32_e32 v101, v101
	v_add_f32_e32 v103, 1.0, v103
	v_exp_f32_e32 v108, v108
	v_rcp_f32_e32 v103, v103
	v_exp_f32_e32 v107, v107
	v_rcp_f32_e32 v106, v106
	v_mul_f32_e32 v102, v88, v102
	v_rcp_f32_e32 v89, v89
	v_mul_f32_e32 v105, v92, v101
	v_add_f32_e32 v108, 1.0, v108
	v_fma_f32 v92, v92, v101, v102
	v_mul_f32_e32 v88, v93, v103
	v_add_f32_e32 v107, 1.0, v107
	v_rcp_f32_e32 v108, v108
	v_add_f32_e32 v92, 0, v92
	v_mul_f32_e32 v101, v102, v102
	v_fma_f32 v93, v93, v103, v104
	v_rcp_f32_e32 v107, v107
	v_mul_f32_e32 v106, v90, v106
	v_fmac_f32_e32 v101, v105, v105
	v_add_f32_e32 v92, v93, v92
	v_mul_f32_e32 v93, v104, v104
	v_mul_f32_e32 v109, v94, v89
	v_fmac_f32_e32 v93, v88, v88
	v_fma_f32 v89, v94, v89, v106
	v_pk_mul_f32 v[80:81], v[80:81], v[100:101] op_sel_hi:[1,0]
	v_add_f32_e32 v93, v101, v93
	v_add_f32_e32 v89, v89, v92
	v_mul_f32_e32 v92, v106, v106
	v_pk_mul_f32 v[84:85], v[84:85], v[100:101] op_sel_hi:[1,0]
	v_pk_mul_f32 v[86:87], v[86:87], v[100:101] op_sel_hi:[1,0]
	v_pk_mul_f32 v[82:83], v[82:83], v[100:101] op_sel_hi:[1,0]
	v_mul_f32_e32 v101, v81, v81
	v_mul_f32_e32 v91, v91, v108
	v_fmac_f32_e32 v92, v109, v109
	v_fmamk_f32 v101, v101, 0xbdd2d3e7, v152
	v_add_f32_e32 v92, v92, v93
	v_fma_f32 v93, v95, v107, v91
	v_mul_f32_e32 v101, v81, v101
	v_mul_f32_e32 v90, v95, v107
	v_add_f32_e32 v93, v93, v89
	v_mul_f32_e32 v89, v91, v91
	v_fmac_f32_e32 v89, v90, v90
	v_add_f32_e32 v92, v89, v92
	v_cvt_pk_bf16_f32 v88, v105, v88
	v_cvt_pk_bf16_f32 v89, v109, v90
	v_cvt_pk_bf16_f32 v90, v102, v104
	v_exp_f32_e32 v101, v101
	v_mul_f32_e32 v103, v86, v86
	v_mul_f32_e32 v104, v82, v82
	v_fmamk_f32 v103, v103, 0xbdd2d3e7, v152
	v_fmamk_f32 v104, v104, 0xbdd2d3e7, v152
	v_mul_f32_e32 v103, v86, v103
	v_mul_f32_e32 v104, v82, v104
	v_mul_f32_e32 v95, v80, v80
	v_mul_f32_e32 v94, v84, v84
	v_fmamk_f32 v95, v95, 0xbdd2d3e7, v152
	v_add_f32_e32 v101, 1.0, v101
	v_fmamk_f32 v94, v94, 0xbdd2d3e7, v152
	v_mul_f32_e32 v95, v80, v95
	v_mul_f32_e32 v100, v85, v85
	v_rcp_f32_e32 v101, v101
	v_exp_f32_e32 v103, v103
	v_exp_f32_e32 v104, v104
	v_mul_f32_e32 v105, v83, v83
	v_mul_f32_e32 v94, v84, v94
	v_fmamk_f32 v100, v100, 0xbdd2d3e7, v152
	v_fmamk_f32 v105, v105, 0xbdd2d3e7, v152
	v_mul_f32_e32 v100, v85, v100
	v_mul_f32_e32 v105, v83, v105
	v_exp_f32_e32 v95, v95
	v_exp_f32_e32 v94, v94
	v_mul_f32_e32 v101, v81, v101
	v_add_f32_e32 v81, 1.0, v103
	v_add_f32_e32 v103, 1.0, v104
	v_mul_f32_e32 v104, v87, v87
	v_exp_f32_e32 v100, v100
	v_fmamk_f32 v104, v104, 0xbdd2d3e7, v152
	v_exp_f32_e32 v105, v105
	v_mul_f32_e32 v104, v87, v104
	v_add_f32_e32 v95, 1.0, v95
	v_add_f32_e32 v94, 1.0, v94
	v_rcp_f32_e32 v95, v95
	v_rcp_f32_e32 v94, v94
	v_add_f32_e32 v100, 1.0, v100
	v_exp_f32_e32 v104, v104
	v_rcp_f32_e32 v103, v103
	v_add_f32_e32 v105, 1.0, v105
	v_rcp_f32_e32 v100, v100
	v_rcp_f32_e32 v105, v105
	v_rcp_f32_e32 v81, v81
	v_mul_f32_e32 v95, v80, v95
	v_add_f32_e32 v104, 1.0, v104
	v_mul_f32_e32 v103, v82, v103
	v_fma_f32 v82, v84, v94, v95
	v_mul_f32_e32 v102, v84, v94
	v_rcp_f32_e32 v104, v104
	v_mul_f32_e32 v105, v83, v105
	v_add_f32_e32 v82, v82, v93
	v_mul_f32_e32 v83, v95, v95
	v_fma_f32 v84, v85, v100, v101
	v_cvt_pk_bf16_f32 v91, v106, v91
	v_mul_f32_e32 v80, v85, v100
	v_mul_f32_e32 v106, v86, v81
	v_fmac_f32_e32 v83, v102, v102
	v_add_f32_e32 v82, v84, v82
	v_mul_f32_e32 v84, v101, v101
	v_fma_f32 v81, v86, v81, v103
	v_add_f32_e32 v83, v83, v92
	v_fmac_f32_e32 v84, v80, v80
	v_add_f32_e32 v81, v81, v82
	v_mul_f32_e32 v82, v103, v103
	v_add_f32_e32 v83, v84, v83
	v_fmac_f32_e32 v82, v106, v106
	v_add_f32_e32 v82, v82, v83
	v_fma_f32 v83, v87, v104, v105
	v_mul_f32_e32 v107, v87, v104
	v_add_f32_e32 v81, v83, v81
	v_mul_f32_e32 v83, v105, v105
	v_fmac_f32_e32 v83, v107, v107
	v_add_f32_e32 v82, v83, v82
	ds_bpermute_b32 v85, v168, v81
	ds_bpermute_b32 v83, v168, v82
	v_lshl_add_u64 v[98:99], s[70:71], 0, v[98:99]
	v_lshl_add_u64 v[98:99], v[160:161], 1, v[98:99]
	global_store_dwordx4 v[98:99], v[88:91], off nt
	v_cvt_pk_bf16_f32 v84, v102, v80
	s_waitcnt lgkmcnt(0)
	v_add_f32_e32 v80, v81, v85
	v_add_f32_e32 v82, v82, v83
	ds_bpermute_b32 v81, v167, v80
	ds_bpermute_b32 v83, v167, v82
	v_cvt_pk_bf16_f32 v85, v106, v107
	v_cvt_pk_bf16_f32 v86, v95, v101
	v_cvt_pk_bf16_f32 v87, v103, v105
	global_store_dwordx4 v[98:99], v[84:87], off offset:256 nt
	s_and_saveexec_b64 s[6:7], s[58:59]
	s_cbranch_execz .LBB0_573
	s_waitcnt lgkmcnt(0)
	v_add_f32_e32 v82, v82, v83
	v_add_f32_e32 v83, v80, v81
	s_lshl_b32 s4, s95, 2
	v_lshlrev_b64 v[80:81], 7, v[96:97]
	s_add_i32 s38, s4, -16
	v_lshl_add_u64 v[80:81], s[72:73], 0, v[80:81]
	v_lshl_add_u64 v[80:81], s[38:39], 2, v[80:81]
	s_lshl_b32 s38, s8, 2
	v_lshl_add_u64 v[80:81], v[80:81], 0, s[38:39]
	global_store_dword v[80:81], v83, off
	global_store_dword v[80:81], v82, off offset:64

.LBB0_577:
	s_waitcnt lgkmcnt(0)
	v_pk_mul_f32 v[76:77], v[76:77], v[84:85] op_sel_hi:[1,0]
	v_lshlrev_b64 v[82:83], 12, v[80:81]
	v_mul_f32_e32 v85, v76, v76
	v_fmamk_f32 v85, v85, 0xbdd2d3e7, v152
	v_mul_f32_e32 v85, v76, v85
	v_exp_f32_e32 v85, v85
	v_mul_f32_e32 v87, v77, v77
	v_fmamk_f32 v87, v87, 0xbdd2d3e7, v152
	v_mul_f32_e32 v87, v77, v87
	v_pk_mul_f32 v[72:73], v[72:73], v[84:85] op_sel_hi:[1,0]
	v_pk_mul_f32 v[78:79], v[78:79], v[84:85] op_sel_hi:[1,0]
	v_mul_f32_e32 v88, v73, v73
	v_fmamk_f32 v88, v88, 0xbdd2d3e7, v152
	v_mul_f32_e32 v88, v73, v88
	v_pk_mul_f32 v[74:75], v[74:75], v[84:85] op_sel_hi:[1,0]
	v_exp_f32_e32 v88, v88
	v_mul_f32_e32 v90, v78, v78
	v_mul_f32_e32 v91, v74, v74
	v_fmamk_f32 v90, v90, 0xbdd2d3e7, v152
	v_fmamk_f32 v91, v91, 0xbdd2d3e7, v152
	v_mul_f32_e32 v86, v72, v72
	v_mul_f32_e32 v90, v78, v90
	v_mul_f32_e32 v91, v74, v91
	v_fmamk_f32 v86, v86, 0xbdd2d3e7, v152
	v_mul_f32_e32 v86, v72, v86
	v_add_f32_e32 v88, 1.0, v88
	v_rcp_f32_e32 v88, v88
	v_exp_f32_e32 v90, v90
	v_exp_f32_e32 v91, v91
	v_exp_f32_e32 v86, v86
	v_mul_f32_e32 v92, v75, v75
	v_exp_f32_e32 v87, v87
	v_mul_f32_e32 v88, v73, v88
	v_add_f32_e32 v73, 1.0, v90
	v_add_f32_e32 v90, 1.0, v91
	v_mul_f32_e32 v91, v79, v79
	v_fmamk_f32 v92, v92, 0xbdd2d3e7, v152
	v_fmamk_f32 v91, v91, 0xbdd2d3e7, v152
	v_mul_f32_e32 v92, v75, v92
	v_add_f32_e32 v86, 1.0, v86
	v_mul_f32_e32 v91, v79, v91
	v_add_f32_e32 v85, 1.0, v85
	v_rcp_f32_e32 v86, v86
	v_rcp_f32_e32 v85, v85
	v_add_f32_e32 v87, 1.0, v87
	v_exp_f32_e32 v92, v92
	v_rcp_f32_e32 v87, v87
	v_exp_f32_e32 v91, v91
	v_rcp_f32_e32 v90, v90
	v_mul_f32_e32 v86, v72, v86
	v_rcp_f32_e32 v73, v73
	v_mul_f32_e32 v89, v76, v85
	v_add_f32_e32 v92, 1.0, v92
	v_fma_f32 v76, v76, v85, v86
	v_mul_f32_e32 v72, v77, v87
	v_add_f32_e32 v91, 1.0, v91
	v_rcp_f32_e32 v92, v92
	v_add_f32_e32 v76, 0, v76
	v_mul_f32_e32 v85, v86, v86
	v_fma_f32 v77, v77, v87, v88
	v_rcp_f32_e32 v91, v91
	v_mul_f32_e32 v90, v74, v90
	v_fmac_f32_e32 v85, v89, v89
	v_add_f32_e32 v76, v77, v76
	v_mul_f32_e32 v77, v88, v88
	v_mul_f32_e32 v93, v78, v73
	v_fmac_f32_e32 v77, v72, v72
	v_fma_f32 v73, v78, v73, v90
	v_pk_mul_f32 v[64:65], v[64:65], v[84:85] op_sel_hi:[1,0]
	v_add_f32_e32 v77, v85, v77
	v_add_f32_e32 v73, v73, v76
	v_mul_f32_e32 v76, v90, v90
	v_pk_mul_f32 v[68:69], v[68:69], v[84:85] op_sel_hi:[1,0]
	v_pk_mul_f32 v[70:71], v[70:71], v[84:85] op_sel_hi:[1,0]
	v_pk_mul_f32 v[66:67], v[66:67], v[84:85] op_sel_hi:[1,0]
	v_mul_f32_e32 v85, v65, v65
	v_mul_f32_e32 v75, v75, v92
	v_fmac_f32_e32 v76, v93, v93
	v_fmamk_f32 v85, v85, 0xbdd2d3e7, v152
	v_add_f32_e32 v76, v76, v77
	v_fma_f32 v77, v79, v91, v75
	v_mul_f32_e32 v85, v65, v85
	v_mul_f32_e32 v74, v79, v91
	v_add_f32_e32 v77, v77, v73
	v_mul_f32_e32 v73, v75, v75
	v_fmac_f32_e32 v73, v74, v74
	v_add_f32_e32 v76, v73, v76
	v_cvt_pk_bf16_f32 v72, v89, v72
	v_cvt_pk_bf16_f32 v73, v93, v74
	v_cvt_pk_bf16_f32 v74, v86, v88
	v_exp_f32_e32 v85, v85
	v_mul_f32_e32 v87, v70, v70
	v_mul_f32_e32 v88, v66, v66
	v_fmamk_f32 v87, v87, 0xbdd2d3e7, v152
	v_fmamk_f32 v88, v88, 0xbdd2d3e7, v152
	v_mul_f32_e32 v87, v70, v87
	v_mul_f32_e32 v88, v66, v88
	v_mul_f32_e32 v79, v64, v64
	v_mul_f32_e32 v78, v68, v68
	v_fmamk_f32 v79, v79, 0xbdd2d3e7, v152
	v_add_f32_e32 v85, 1.0, v85
	v_fmamk_f32 v78, v78, 0xbdd2d3e7, v152
	v_mul_f32_e32 v79, v64, v79
	v_mul_f32_e32 v84, v69, v69
	v_rcp_f32_e32 v85, v85
	v_exp_f32_e32 v87, v87
	v_exp_f32_e32 v88, v88
	v_mul_f32_e32 v89, v67, v67
	v_mul_f32_e32 v78, v68, v78
	v_fmamk_f32 v84, v84, 0xbdd2d3e7, v152
	v_fmamk_f32 v89, v89, 0xbdd2d3e7, v152
	v_mul_f32_e32 v84, v69, v84
	v_mul_f32_e32 v89, v67, v89
	v_exp_f32_e32 v79, v79
	v_exp_f32_e32 v78, v78
	v_mul_f32_e32 v85, v65, v85
	v_add_f32_e32 v65, 1.0, v87
	v_add_f32_e32 v87, 1.0, v88
	v_mul_f32_e32 v88, v71, v71
	v_exp_f32_e32 v84, v84
	v_fmamk_f32 v88, v88, 0xbdd2d3e7, v152
	v_exp_f32_e32 v89, v89
	v_mul_f32_e32 v88, v71, v88
	v_add_f32_e32 v79, 1.0, v79
	v_add_f32_e32 v78, 1.0, v78
	v_rcp_f32_e32 v79, v79
	v_rcp_f32_e32 v78, v78
	v_add_f32_e32 v84, 1.0, v84
	v_exp_f32_e32 v88, v88
	v_rcp_f32_e32 v87, v87
	v_add_f32_e32 v89, 1.0, v89
	v_rcp_f32_e32 v84, v84
	v_rcp_f32_e32 v89, v89
	v_rcp_f32_e32 v65, v65
	v_mul_f32_e32 v79, v64, v79
	v_add_f32_e32 v88, 1.0, v88
	v_mul_f32_e32 v87, v66, v87
	v_fma_f32 v66, v68, v78, v79
	v_mul_f32_e32 v86, v68, v78
	v_rcp_f32_e32 v88, v88
	v_mul_f32_e32 v89, v67, v89
	v_add_f32_e32 v66, v66, v77
	v_mul_f32_e32 v67, v79, v79
	v_fma_f32 v68, v69, v84, v85
	v_cvt_pk_bf16_f32 v75, v90, v75
	v_mul_f32_e32 v64, v69, v84
	v_mul_f32_e32 v90, v70, v65
	v_fmac_f32_e32 v67, v86, v86
	v_add_f32_e32 v66, v68, v66
	v_mul_f32_e32 v68, v85, v85
	v_fma_f32 v65, v70, v65, v87
	v_add_f32_e32 v67, v67, v76
	v_fmac_f32_e32 v68, v64, v64
	v_add_f32_e32 v65, v65, v66
	v_mul_f32_e32 v66, v87, v87
	v_add_f32_e32 v67, v68, v67
	v_fmac_f32_e32 v66, v90, v90
	v_add_f32_e32 v66, v66, v67
	v_fma_f32 v67, v71, v88, v89
	v_mul_f32_e32 v91, v71, v88
	v_add_f32_e32 v65, v67, v65
	v_mul_f32_e32 v67, v89, v89
	v_fmac_f32_e32 v67, v91, v91
	v_add_f32_e32 v66, v67, v66
	ds_bpermute_b32 v69, v168, v65
	ds_bpermute_b32 v67, v168, v66
	v_lshl_add_u64 v[82:83], s[70:71], 0, v[82:83]
	v_lshl_add_u64 v[82:83], v[160:161], 1, v[82:83]
	global_store_dwordx4 v[82:83], v[72:75], off nt
	v_cvt_pk_bf16_f32 v68, v86, v64
	s_waitcnt lgkmcnt(0)
	v_add_f32_e32 v64, v65, v69
	v_add_f32_e32 v66, v66, v67
	ds_bpermute_b32 v65, v167, v64
	ds_bpermute_b32 v67, v167, v66
	v_cvt_pk_bf16_f32 v69, v90, v91
	v_cvt_pk_bf16_f32 v70, v79, v85
	v_cvt_pk_bf16_f32 v71, v87, v89
	global_store_dwordx4 v[82:83], v[68:71], off offset:256 nt
	s_and_saveexec_b64 s[6:7], s[58:59]
	s_cbranch_execz .LBB0_579
	s_waitcnt lgkmcnt(0)
	v_add_f32_e32 v66, v66, v67
	v_add_f32_e32 v67, v64, v65
	s_lshl_b32 s4, s95, 2
	v_lshlrev_b64 v[64:65], 7, v[80:81]
	s_add_i32 s38, s4, -16
	v_lshl_add_u64 v[64:65], s[72:73], 0, v[64:65]
	v_lshl_add_u64 v[64:65], s[38:39], 2, v[64:65]
	s_lshl_b32 s38, s8, 2
	v_lshl_add_u64 v[64:65], v[64:65], 0, s[38:39]
	global_store_dword v[64:65], v67, off
	global_store_dword v[64:65], v66, off offset:64

.LBB0_583:
	s_waitcnt lgkmcnt(0)
	v_pk_mul_f32 v[60:61], v[60:61], v[68:69] op_sel_hi:[1,0]
	v_lshlrev_b64 v[66:67], 12, v[64:65]
	v_mul_f32_e32 v69, v60, v60
	v_fmamk_f32 v69, v69, 0xbdd2d3e7, v152
	v_mul_f32_e32 v69, v60, v69
	v_exp_f32_e32 v69, v69
	v_mul_f32_e32 v71, v61, v61
	v_fmamk_f32 v71, v71, 0xbdd2d3e7, v152
	v_mul_f32_e32 v71, v61, v71
	v_pk_mul_f32 v[56:57], v[56:57], v[68:69] op_sel_hi:[1,0]
	v_pk_mul_f32 v[62:63], v[62:63], v[68:69] op_sel_hi:[1,0]
	v_mul_f32_e32 v72, v57, v57
	v_fmamk_f32 v72, v72, 0xbdd2d3e7, v152
	v_mul_f32_e32 v72, v57, v72
	v_pk_mul_f32 v[58:59], v[58:59], v[68:69] op_sel_hi:[1,0]
	v_exp_f32_e32 v72, v72
	v_mul_f32_e32 v74, v62, v62
	v_mul_f32_e32 v75, v58, v58
	v_fmamk_f32 v74, v74, 0xbdd2d3e7, v152
	v_fmamk_f32 v75, v75, 0xbdd2d3e7, v152
	v_mul_f32_e32 v70, v56, v56
	v_mul_f32_e32 v74, v62, v74
	v_mul_f32_e32 v75, v58, v75
	v_fmamk_f32 v70, v70, 0xbdd2d3e7, v152
	v_mul_f32_e32 v70, v56, v70
	v_add_f32_e32 v72, 1.0, v72
	v_rcp_f32_e32 v72, v72
	v_exp_f32_e32 v74, v74
	v_exp_f32_e32 v75, v75
	v_exp_f32_e32 v70, v70
	v_mul_f32_e32 v76, v59, v59
	v_exp_f32_e32 v71, v71
	v_mul_f32_e32 v72, v57, v72
	v_add_f32_e32 v57, 1.0, v74
	v_add_f32_e32 v74, 1.0, v75
	v_mul_f32_e32 v75, v63, v63
	v_fmamk_f32 v76, v76, 0xbdd2d3e7, v152
	v_fmamk_f32 v75, v75, 0xbdd2d3e7, v152
	v_mul_f32_e32 v76, v59, v76
	v_add_f32_e32 v70, 1.0, v70
	v_mul_f32_e32 v75, v63, v75
	v_add_f32_e32 v69, 1.0, v69
	v_rcp_f32_e32 v70, v70
	v_rcp_f32_e32 v69, v69
	v_add_f32_e32 v71, 1.0, v71
	v_exp_f32_e32 v76, v76
	v_rcp_f32_e32 v71, v71
	v_exp_f32_e32 v75, v75
	v_rcp_f32_e32 v74, v74
	v_mul_f32_e32 v70, v56, v70
	v_rcp_f32_e32 v57, v57
	v_mul_f32_e32 v73, v60, v69
	v_add_f32_e32 v76, 1.0, v76
	v_fma_f32 v60, v60, v69, v70
	v_mul_f32_e32 v56, v61, v71
	v_add_f32_e32 v75, 1.0, v75
	v_rcp_f32_e32 v76, v76
	v_add_f32_e32 v60, 0, v60
	v_mul_f32_e32 v69, v70, v70
	v_fma_f32 v61, v61, v71, v72
	v_rcp_f32_e32 v75, v75
	v_mul_f32_e32 v74, v58, v74
	v_fmac_f32_e32 v69, v73, v73
	v_add_f32_e32 v60, v61, v60
	v_mul_f32_e32 v61, v72, v72
	v_mul_f32_e32 v77, v62, v57
	v_fmac_f32_e32 v61, v56, v56
	v_fma_f32 v57, v62, v57, v74
	v_pk_mul_f32 v[48:49], v[48:49], v[68:69] op_sel_hi:[1,0]
	v_add_f32_e32 v61, v69, v61
	v_add_f32_e32 v57, v57, v60
	v_mul_f32_e32 v60, v74, v74
	v_pk_mul_f32 v[52:53], v[52:53], v[68:69] op_sel_hi:[1,0]
	v_pk_mul_f32 v[54:55], v[54:55], v[68:69] op_sel_hi:[1,0]
	v_pk_mul_f32 v[50:51], v[50:51], v[68:69] op_sel_hi:[1,0]
	v_mul_f32_e32 v69, v49, v49
	v_mul_f32_e32 v59, v59, v76
	v_fmac_f32_e32 v60, v77, v77
	v_fmamk_f32 v69, v69, 0xbdd2d3e7, v152
	v_add_f32_e32 v60, v60, v61
	v_fma_f32 v61, v63, v75, v59
	v_mul_f32_e32 v69, v49, v69
	v_mul_f32_e32 v58, v63, v75
	v_add_f32_e32 v61, v61, v57
	v_mul_f32_e32 v57, v59, v59
	v_fmac_f32_e32 v57, v58, v58
	v_add_f32_e32 v60, v57, v60
	v_cvt_pk_bf16_f32 v56, v73, v56
	v_cvt_pk_bf16_f32 v57, v77, v58
	v_cvt_pk_bf16_f32 v58, v70, v72
	v_exp_f32_e32 v69, v69
	v_mul_f32_e32 v71, v54, v54
	v_mul_f32_e32 v72, v50, v50
	v_fmamk_f32 v71, v71, 0xbdd2d3e7, v152
	v_fmamk_f32 v72, v72, 0xbdd2d3e7, v152
	v_mul_f32_e32 v71, v54, v71
	v_mul_f32_e32 v72, v50, v72
	v_mul_f32_e32 v63, v48, v48
	v_mul_f32_e32 v62, v52, v52
	v_fmamk_f32 v63, v63, 0xbdd2d3e7, v152
	v_add_f32_e32 v69, 1.0, v69
	v_fmamk_f32 v62, v62, 0xbdd2d3e7, v152
	v_mul_f32_e32 v63, v48, v63
	v_mul_f32_e32 v68, v53, v53
	v_rcp_f32_e32 v69, v69
	v_exp_f32_e32 v71, v71
	v_exp_f32_e32 v72, v72
	v_mul_f32_e32 v73, v51, v51
	v_mul_f32_e32 v62, v52, v62
	v_fmamk_f32 v68, v68, 0xbdd2d3e7, v152
	v_fmamk_f32 v73, v73, 0xbdd2d3e7, v152
	v_mul_f32_e32 v68, v53, v68
	v_mul_f32_e32 v73, v51, v73
	v_exp_f32_e32 v63, v63
	v_exp_f32_e32 v62, v62
	v_mul_f32_e32 v69, v49, v69
	v_add_f32_e32 v49, 1.0, v71
	v_add_f32_e32 v71, 1.0, v72
	v_mul_f32_e32 v72, v55, v55
	v_exp_f32_e32 v68, v68
	v_fmamk_f32 v72, v72, 0xbdd2d3e7, v152
	v_exp_f32_e32 v73, v73
	v_mul_f32_e32 v72, v55, v72
	v_add_f32_e32 v63, 1.0, v63
	v_add_f32_e32 v62, 1.0, v62
	v_rcp_f32_e32 v63, v63
	v_rcp_f32_e32 v62, v62
	v_add_f32_e32 v68, 1.0, v68
	v_exp_f32_e32 v72, v72
	v_rcp_f32_e32 v71, v71
	v_add_f32_e32 v73, 1.0, v73
	v_rcp_f32_e32 v68, v68
	v_rcp_f32_e32 v73, v73
	v_rcp_f32_e32 v49, v49
	v_mul_f32_e32 v63, v48, v63
	v_add_f32_e32 v72, 1.0, v72
	v_mul_f32_e32 v71, v50, v71
	v_fma_f32 v50, v52, v62, v63
	v_mul_f32_e32 v70, v52, v62
	v_rcp_f32_e32 v72, v72
	v_mul_f32_e32 v73, v51, v73
	v_add_f32_e32 v50, v50, v61
	v_mul_f32_e32 v51, v63, v63
	v_fma_f32 v52, v53, v68, v69
	v_cvt_pk_bf16_f32 v59, v74, v59
	v_mul_f32_e32 v48, v53, v68
	v_mul_f32_e32 v74, v54, v49
	v_fmac_f32_e32 v51, v70, v70
	v_add_f32_e32 v50, v52, v50
	v_mul_f32_e32 v52, v69, v69
	v_fma_f32 v49, v54, v49, v71
	v_add_f32_e32 v51, v51, v60
	v_fmac_f32_e32 v52, v48, v48
	v_add_f32_e32 v49, v49, v50
	v_mul_f32_e32 v50, v71, v71
	v_add_f32_e32 v51, v52, v51
	v_fmac_f32_e32 v50, v74, v74
	v_add_f32_e32 v50, v50, v51
	v_fma_f32 v51, v55, v72, v73
	v_mul_f32_e32 v75, v55, v72
	v_add_f32_e32 v49, v51, v49
	v_mul_f32_e32 v51, v73, v73
	v_fmac_f32_e32 v51, v75, v75
	v_add_f32_e32 v50, v51, v50
	ds_bpermute_b32 v53, v168, v49
	ds_bpermute_b32 v51, v168, v50
	v_lshl_add_u64 v[66:67], s[70:71], 0, v[66:67]
	v_lshl_add_u64 v[66:67], v[160:161], 1, v[66:67]
	global_store_dwordx4 v[66:67], v[56:59], off nt
	v_cvt_pk_bf16_f32 v52, v70, v48
	s_waitcnt lgkmcnt(0)
	v_add_f32_e32 v48, v49, v53
	v_add_f32_e32 v50, v50, v51
	ds_bpermute_b32 v49, v167, v48
	ds_bpermute_b32 v51, v167, v50
	v_cvt_pk_bf16_f32 v53, v74, v75
	v_cvt_pk_bf16_f32 v54, v63, v69
	v_cvt_pk_bf16_f32 v55, v71, v73
	global_store_dwordx4 v[66:67], v[52:55], off offset:256 nt
	s_and_saveexec_b64 s[6:7], s[58:59]
	s_cbranch_execz .LBB0_585
	s_waitcnt lgkmcnt(0)
	v_add_f32_e32 v50, v50, v51
	v_add_f32_e32 v51, v48, v49
	s_lshl_b32 s4, s95, 2
	v_lshlrev_b64 v[48:49], 7, v[64:65]
	s_add_i32 s38, s4, -16
	v_lshl_add_u64 v[48:49], s[72:73], 0, v[48:49]
	v_lshl_add_u64 v[48:49], s[38:39], 2, v[48:49]
	s_lshl_b32 s38, s8, 2
	v_lshl_add_u64 v[48:49], v[48:49], 0, s[38:39]
	global_store_dword v[48:49], v51, off
	global_store_dword v[48:49], v50, off offset:64

.LBB0_589:
	s_waitcnt lgkmcnt(0)
	v_pk_mul_f32 v[44:45], v[44:45], v[52:53] op_sel_hi:[1,0]
	v_lshlrev_b64 v[50:51], 12, v[48:49]
	v_mul_f32_e32 v53, v44, v44
	v_fmamk_f32 v53, v53, 0xbdd2d3e7, v152
	v_mul_f32_e32 v53, v44, v53
	v_exp_f32_e32 v53, v53
	v_mul_f32_e32 v55, v45, v45
	v_fmamk_f32 v55, v55, 0xbdd2d3e7, v152
	v_mul_f32_e32 v55, v45, v55
	v_pk_mul_f32 v[40:41], v[40:41], v[52:53] op_sel_hi:[1,0]
	v_pk_mul_f32 v[46:47], v[46:47], v[52:53] op_sel_hi:[1,0]
	v_mul_f32_e32 v56, v41, v41
	v_fmamk_f32 v56, v56, 0xbdd2d3e7, v152
	v_mul_f32_e32 v56, v41, v56
	v_pk_mul_f32 v[42:43], v[42:43], v[52:53] op_sel_hi:[1,0]
	v_exp_f32_e32 v56, v56
	v_mul_f32_e32 v58, v46, v46
	v_mul_f32_e32 v59, v42, v42
	v_fmamk_f32 v58, v58, 0xbdd2d3e7, v152
	v_fmamk_f32 v59, v59, 0xbdd2d3e7, v152
	v_mul_f32_e32 v54, v40, v40
	v_mul_f32_e32 v58, v46, v58
	v_mul_f32_e32 v59, v42, v59
	v_fmamk_f32 v54, v54, 0xbdd2d3e7, v152
	v_mul_f32_e32 v54, v40, v54
	v_add_f32_e32 v56, 1.0, v56
	v_rcp_f32_e32 v56, v56
	v_exp_f32_e32 v58, v58
	v_exp_f32_e32 v59, v59
	v_exp_f32_e32 v54, v54
	v_mul_f32_e32 v60, v43, v43
	v_exp_f32_e32 v55, v55
	v_mul_f32_e32 v56, v41, v56
	v_add_f32_e32 v41, 1.0, v58
	v_add_f32_e32 v58, 1.0, v59
	v_mul_f32_e32 v59, v47, v47
	v_fmamk_f32 v60, v60, 0xbdd2d3e7, v152
	v_fmamk_f32 v59, v59, 0xbdd2d3e7, v152
	v_mul_f32_e32 v60, v43, v60
	v_add_f32_e32 v54, 1.0, v54
	v_mul_f32_e32 v59, v47, v59
	v_add_f32_e32 v53, 1.0, v53
	v_rcp_f32_e32 v54, v54
	v_rcp_f32_e32 v53, v53
	v_add_f32_e32 v55, 1.0, v55
	v_exp_f32_e32 v60, v60
	v_rcp_f32_e32 v55, v55
	v_exp_f32_e32 v59, v59
	v_rcp_f32_e32 v58, v58
	v_mul_f32_e32 v54, v40, v54
	v_rcp_f32_e32 v41, v41
	v_mul_f32_e32 v57, v44, v53
	v_add_f32_e32 v60, 1.0, v60
	v_fma_f32 v44, v44, v53, v54
	v_mul_f32_e32 v40, v45, v55
	v_add_f32_e32 v59, 1.0, v59
	v_rcp_f32_e32 v60, v60
	v_add_f32_e32 v44, 0, v44
	v_mul_f32_e32 v53, v54, v54
	v_fma_f32 v45, v45, v55, v56
	v_rcp_f32_e32 v59, v59
	v_mul_f32_e32 v58, v42, v58
	v_fmac_f32_e32 v53, v57, v57
	v_add_f32_e32 v44, v45, v44
	v_mul_f32_e32 v45, v56, v56
	v_mul_f32_e32 v61, v46, v41
	v_fmac_f32_e32 v45, v40, v40
	v_fma_f32 v41, v46, v41, v58
	v_pk_mul_f32 v[32:33], v[32:33], v[52:53] op_sel_hi:[1,0]
	v_add_f32_e32 v45, v53, v45
	v_add_f32_e32 v41, v41, v44
	v_mul_f32_e32 v44, v58, v58
	v_pk_mul_f32 v[36:37], v[36:37], v[52:53] op_sel_hi:[1,0]
	v_pk_mul_f32 v[38:39], v[38:39], v[52:53] op_sel_hi:[1,0]
	v_pk_mul_f32 v[34:35], v[34:35], v[52:53] op_sel_hi:[1,0]
	v_mul_f32_e32 v53, v33, v33
	v_mul_f32_e32 v43, v43, v60
	v_fmac_f32_e32 v44, v61, v61
	v_fmamk_f32 v53, v53, 0xbdd2d3e7, v152
	v_add_f32_e32 v44, v44, v45
	v_fma_f32 v45, v47, v59, v43
	v_mul_f32_e32 v53, v33, v53
	v_mul_f32_e32 v42, v47, v59
	v_add_f32_e32 v45, v45, v41
	v_mul_f32_e32 v41, v43, v43
	v_fmac_f32_e32 v41, v42, v42
	v_add_f32_e32 v44, v41, v44
	v_cvt_pk_bf16_f32 v40, v57, v40
	v_cvt_pk_bf16_f32 v41, v61, v42
	v_cvt_pk_bf16_f32 v42, v54, v56
	v_exp_f32_e32 v53, v53
	v_mul_f32_e32 v55, v38, v38
	v_mul_f32_e32 v56, v34, v34
	v_fmamk_f32 v55, v55, 0xbdd2d3e7, v152
	v_fmamk_f32 v56, v56, 0xbdd2d3e7, v152
	v_mul_f32_e32 v55, v38, v55
	v_mul_f32_e32 v56, v34, v56
	v_mul_f32_e32 v47, v32, v32
	v_mul_f32_e32 v46, v36, v36
	v_fmamk_f32 v47, v47, 0xbdd2d3e7, v152
	v_add_f32_e32 v53, 1.0, v53
	v_fmamk_f32 v46, v46, 0xbdd2d3e7, v152
	v_mul_f32_e32 v47, v32, v47
	v_mul_f32_e32 v52, v37, v37
	v_rcp_f32_e32 v53, v53
	v_exp_f32_e32 v55, v55
	v_exp_f32_e32 v56, v56
	v_mul_f32_e32 v57, v35, v35
	v_mul_f32_e32 v46, v36, v46
	v_fmamk_f32 v52, v52, 0xbdd2d3e7, v152
	v_fmamk_f32 v57, v57, 0xbdd2d3e7, v152
	v_mul_f32_e32 v52, v37, v52
	v_mul_f32_e32 v57, v35, v57
	v_exp_f32_e32 v47, v47
	v_exp_f32_e32 v46, v46
	v_mul_f32_e32 v53, v33, v53
	v_add_f32_e32 v33, 1.0, v55
	v_add_f32_e32 v55, 1.0, v56
	v_mul_f32_e32 v56, v39, v39
	v_exp_f32_e32 v52, v52
	v_fmamk_f32 v56, v56, 0xbdd2d3e7, v152
	v_exp_f32_e32 v57, v57
	v_mul_f32_e32 v56, v39, v56
	v_add_f32_e32 v47, 1.0, v47
	v_add_f32_e32 v46, 1.0, v46
	v_rcp_f32_e32 v47, v47
	v_rcp_f32_e32 v46, v46
	v_add_f32_e32 v52, 1.0, v52
	v_exp_f32_e32 v56, v56
	v_rcp_f32_e32 v55, v55
	v_add_f32_e32 v57, 1.0, v57
	v_rcp_f32_e32 v52, v52
	v_rcp_f32_e32 v57, v57
	v_rcp_f32_e32 v33, v33
	v_mul_f32_e32 v47, v32, v47
	v_add_f32_e32 v56, 1.0, v56
	v_mul_f32_e32 v55, v34, v55
	v_fma_f32 v34, v36, v46, v47
	v_mul_f32_e32 v54, v36, v46
	v_rcp_f32_e32 v56, v56
	v_mul_f32_e32 v57, v35, v57
	v_add_f32_e32 v34, v34, v45
	v_mul_f32_e32 v35, v47, v47
	v_fma_f32 v36, v37, v52, v53
	v_cvt_pk_bf16_f32 v43, v58, v43
	v_mul_f32_e32 v32, v37, v52
	v_mul_f32_e32 v58, v38, v33
	v_fmac_f32_e32 v35, v54, v54
	v_add_f32_e32 v34, v36, v34
	v_mul_f32_e32 v36, v53, v53
	v_fma_f32 v33, v38, v33, v55
	v_add_f32_e32 v35, v35, v44
	v_fmac_f32_e32 v36, v32, v32
	v_add_f32_e32 v33, v33, v34
	v_mul_f32_e32 v34, v55, v55
	v_add_f32_e32 v35, v36, v35
	v_fmac_f32_e32 v34, v58, v58
	v_add_f32_e32 v34, v34, v35
	v_fma_f32 v35, v39, v56, v57
	v_mul_f32_e32 v59, v39, v56
	v_add_f32_e32 v33, v35, v33
	v_mul_f32_e32 v35, v57, v57
	v_fmac_f32_e32 v35, v59, v59
	v_add_f32_e32 v34, v35, v34
	ds_bpermute_b32 v37, v168, v33
	ds_bpermute_b32 v35, v168, v34
	v_lshl_add_u64 v[50:51], s[70:71], 0, v[50:51]
	v_lshl_add_u64 v[50:51], v[160:161], 1, v[50:51]
	global_store_dwordx4 v[50:51], v[40:43], off nt
	v_cvt_pk_bf16_f32 v36, v54, v32
	s_waitcnt lgkmcnt(0)
	v_add_f32_e32 v32, v33, v37
	v_add_f32_e32 v34, v34, v35
	ds_bpermute_b32 v33, v167, v32
	ds_bpermute_b32 v35, v167, v34
	v_cvt_pk_bf16_f32 v37, v58, v59
	v_cvt_pk_bf16_f32 v38, v47, v53
	v_cvt_pk_bf16_f32 v39, v55, v57
	global_store_dwordx4 v[50:51], v[36:39], off offset:256 nt
	s_and_saveexec_b64 s[6:7], s[58:59]
	s_cbranch_execz .LBB0_591
	s_waitcnt lgkmcnt(0)
	v_add_f32_e32 v34, v34, v35
	v_add_f32_e32 v35, v32, v33
	s_lshl_b32 s4, s95, 2
	v_lshlrev_b64 v[32:33], 7, v[48:49]
	s_add_i32 s38, s4, -16
	v_lshl_add_u64 v[32:33], s[72:73], 0, v[32:33]
	v_lshl_add_u64 v[32:33], s[38:39], 2, v[32:33]
	s_lshl_b32 s38, s8, 2
	v_lshl_add_u64 v[32:33], v[32:33], 0, s[38:39]
	global_store_dword v[32:33], v35, off
	global_store_dword v[32:33], v34, off offset:64

.LBB0_595:
	s_waitcnt lgkmcnt(0)
	v_pk_mul_f32 v[28:29], v[28:29], v[36:37] op_sel_hi:[1,0]
	v_lshlrev_b64 v[34:35], 12, v[32:33]
	v_mul_f32_e32 v37, v28, v28
	v_fmamk_f32 v37, v37, 0xbdd2d3e7, v152
	v_mul_f32_e32 v37, v28, v37
	v_exp_f32_e32 v37, v37
	v_mul_f32_e32 v39, v29, v29
	v_fmamk_f32 v39, v39, 0xbdd2d3e7, v152
	v_mul_f32_e32 v39, v29, v39
	v_pk_mul_f32 v[24:25], v[24:25], v[36:37] op_sel_hi:[1,0]
	v_pk_mul_f32 v[30:31], v[30:31], v[36:37] op_sel_hi:[1,0]
	v_mul_f32_e32 v40, v25, v25
	v_fmamk_f32 v40, v40, 0xbdd2d3e7, v152
	v_mul_f32_e32 v40, v25, v40
	v_pk_mul_f32 v[26:27], v[26:27], v[36:37] op_sel_hi:[1,0]
	v_exp_f32_e32 v40, v40
	v_mul_f32_e32 v42, v30, v30
	v_mul_f32_e32 v43, v26, v26
	v_fmamk_f32 v42, v42, 0xbdd2d3e7, v152
	v_fmamk_f32 v43, v43, 0xbdd2d3e7, v152
	v_mul_f32_e32 v38, v24, v24
	v_mul_f32_e32 v42, v30, v42
	v_mul_f32_e32 v43, v26, v43
	v_fmamk_f32 v38, v38, 0xbdd2d3e7, v152
	v_mul_f32_e32 v38, v24, v38
	v_add_f32_e32 v40, 1.0, v40
	v_rcp_f32_e32 v40, v40
	v_exp_f32_e32 v42, v42
	v_exp_f32_e32 v43, v43
	v_exp_f32_e32 v38, v38
	v_mul_f32_e32 v44, v27, v27
	v_exp_f32_e32 v39, v39
	v_mul_f32_e32 v40, v25, v40
	v_add_f32_e32 v25, 1.0, v42
	v_add_f32_e32 v42, 1.0, v43
	v_mul_f32_e32 v43, v31, v31
	v_fmamk_f32 v44, v44, 0xbdd2d3e7, v152
	v_fmamk_f32 v43, v43, 0xbdd2d3e7, v152
	v_mul_f32_e32 v44, v27, v44
	v_add_f32_e32 v38, 1.0, v38
	v_mul_f32_e32 v43, v31, v43
	v_add_f32_e32 v37, 1.0, v37
	v_rcp_f32_e32 v38, v38
	v_rcp_f32_e32 v37, v37
	v_add_f32_e32 v39, 1.0, v39
	v_exp_f32_e32 v44, v44
	v_rcp_f32_e32 v39, v39
	v_exp_f32_e32 v43, v43
	v_rcp_f32_e32 v42, v42
	v_mul_f32_e32 v38, v24, v38
	v_rcp_f32_e32 v25, v25
	v_mul_f32_e32 v41, v28, v37
	v_add_f32_e32 v44, 1.0, v44
	v_fma_f32 v28, v28, v37, v38
	v_mul_f32_e32 v24, v29, v39
	v_add_f32_e32 v43, 1.0, v43
	v_rcp_f32_e32 v44, v44
	v_add_f32_e32 v28, 0, v28
	v_mul_f32_e32 v37, v38, v38
	v_fma_f32 v29, v29, v39, v40
	v_rcp_f32_e32 v43, v43
	v_mul_f32_e32 v42, v26, v42
	v_fmac_f32_e32 v37, v41, v41
	v_add_f32_e32 v28, v29, v28
	v_mul_f32_e32 v29, v40, v40
	v_mul_f32_e32 v45, v30, v25
	v_fmac_f32_e32 v29, v24, v24
	v_fma_f32 v25, v30, v25, v42
	v_pk_mul_f32 v[16:17], v[16:17], v[36:37] op_sel_hi:[1,0]
	v_add_f32_e32 v29, v37, v29
	v_add_f32_e32 v25, v25, v28
	v_mul_f32_e32 v28, v42, v42
	v_pk_mul_f32 v[20:21], v[20:21], v[36:37] op_sel_hi:[1,0]
	v_pk_mul_f32 v[22:23], v[22:23], v[36:37] op_sel_hi:[1,0]
	v_pk_mul_f32 v[18:19], v[18:19], v[36:37] op_sel_hi:[1,0]
	v_mul_f32_e32 v37, v17, v17
	v_mul_f32_e32 v27, v27, v44
	v_fmac_f32_e32 v28, v45, v45
	v_fmamk_f32 v37, v37, 0xbdd2d3e7, v152
	v_add_f32_e32 v28, v28, v29
	v_fma_f32 v29, v31, v43, v27
	v_mul_f32_e32 v37, v17, v37
	v_mul_f32_e32 v26, v31, v43
	v_add_f32_e32 v29, v29, v25
	v_mul_f32_e32 v25, v27, v27
	v_fmac_f32_e32 v25, v26, v26
	v_add_f32_e32 v28, v25, v28
	v_cvt_pk_bf16_f32 v24, v41, v24
	v_cvt_pk_bf16_f32 v25, v45, v26
	v_cvt_pk_bf16_f32 v26, v38, v40
	v_exp_f32_e32 v37, v37
	v_mul_f32_e32 v39, v22, v22
	v_mul_f32_e32 v40, v18, v18
	v_fmamk_f32 v39, v39, 0xbdd2d3e7, v152
	v_fmamk_f32 v40, v40, 0xbdd2d3e7, v152
	v_mul_f32_e32 v39, v22, v39
	v_mul_f32_e32 v40, v18, v40
	v_mul_f32_e32 v31, v16, v16
	v_mul_f32_e32 v30, v20, v20
	v_fmamk_f32 v31, v31, 0xbdd2d3e7, v152
	v_add_f32_e32 v37, 1.0, v37
	v_fmamk_f32 v30, v30, 0xbdd2d3e7, v152
	v_mul_f32_e32 v31, v16, v31
	v_mul_f32_e32 v36, v21, v21
	v_rcp_f32_e32 v37, v37
	v_exp_f32_e32 v39, v39
	v_exp_f32_e32 v40, v40
	v_mul_f32_e32 v41, v19, v19
	v_mul_f32_e32 v30, v20, v30
	v_fmamk_f32 v36, v36, 0xbdd2d3e7, v152
	v_fmamk_f32 v41, v41, 0xbdd2d3e7, v152
	v_mul_f32_e32 v36, v21, v36
	v_mul_f32_e32 v41, v19, v41
	v_exp_f32_e32 v31, v31
	v_exp_f32_e32 v30, v30
	v_mul_f32_e32 v37, v17, v37
	v_add_f32_e32 v17, 1.0, v39
	v_add_f32_e32 v39, 1.0, v40
	v_mul_f32_e32 v40, v23, v23
	v_exp_f32_e32 v36, v36
	v_fmamk_f32 v40, v40, 0xbdd2d3e7, v152
	v_exp_f32_e32 v41, v41
	v_mul_f32_e32 v40, v23, v40
	v_add_f32_e32 v31, 1.0, v31
	v_add_f32_e32 v30, 1.0, v30
	v_rcp_f32_e32 v31, v31
	v_rcp_f32_e32 v30, v30
	v_add_f32_e32 v36, 1.0, v36
	v_exp_f32_e32 v40, v40
	v_rcp_f32_e32 v39, v39
	v_add_f32_e32 v41, 1.0, v41
	v_rcp_f32_e32 v36, v36
	v_rcp_f32_e32 v41, v41
	v_rcp_f32_e32 v17, v17
	v_mul_f32_e32 v31, v16, v31
	v_add_f32_e32 v40, 1.0, v40
	v_mul_f32_e32 v39, v18, v39
	v_fma_f32 v18, v20, v30, v31
	v_mul_f32_e32 v38, v20, v30
	v_rcp_f32_e32 v40, v40
	v_mul_f32_e32 v41, v19, v41
	v_add_f32_e32 v18, v18, v29
	v_mul_f32_e32 v19, v31, v31
	v_fma_f32 v20, v21, v36, v37
	v_cvt_pk_bf16_f32 v27, v42, v27
	v_mul_f32_e32 v16, v21, v36
	v_mul_f32_e32 v42, v22, v17
	v_fmac_f32_e32 v19, v38, v38
	v_add_f32_e32 v18, v20, v18
	v_mul_f32_e32 v20, v37, v37
	v_fma_f32 v17, v22, v17, v39
	v_add_f32_e32 v19, v19, v28
	v_fmac_f32_e32 v20, v16, v16
	v_add_f32_e32 v17, v17, v18
	v_mul_f32_e32 v18, v39, v39
	v_add_f32_e32 v19, v20, v19
	v_fmac_f32_e32 v18, v42, v42
	v_add_f32_e32 v18, v18, v19
	v_fma_f32 v19, v23, v40, v41
	v_mul_f32_e32 v43, v23, v40
	v_add_f32_e32 v17, v19, v17
	v_mul_f32_e32 v19, v41, v41
	v_fmac_f32_e32 v19, v43, v43
	v_add_f32_e32 v18, v19, v18
	ds_bpermute_b32 v21, v168, v17
	ds_bpermute_b32 v19, v168, v18
	v_lshl_add_u64 v[34:35], s[70:71], 0, v[34:35]
	v_lshl_add_u64 v[34:35], v[160:161], 1, v[34:35]
	global_store_dwordx4 v[34:35], v[24:27], off nt
	v_cvt_pk_bf16_f32 v20, v38, v16
	s_waitcnt lgkmcnt(0)
	v_add_f32_e32 v16, v17, v21
	v_add_f32_e32 v18, v18, v19
	ds_bpermute_b32 v17, v167, v16
	ds_bpermute_b32 v19, v167, v18
	v_cvt_pk_bf16_f32 v21, v42, v43
	v_cvt_pk_bf16_f32 v22, v31, v37
	v_cvt_pk_bf16_f32 v23, v39, v41
	global_store_dwordx4 v[34:35], v[20:23], off offset:256 nt
	s_and_saveexec_b64 s[6:7], s[58:59]
	s_cbranch_execz .LBB0_597
	s_waitcnt lgkmcnt(0)
	v_add_f32_e32 v18, v18, v19
	v_add_f32_e32 v19, v16, v17
	s_lshl_b32 s4, s95, 2
	v_lshlrev_b64 v[16:17], 7, v[32:33]
	s_add_i32 s38, s4, -16
	v_lshl_add_u64 v[16:17], s[72:73], 0, v[16:17]
	v_lshl_add_u64 v[16:17], s[38:39], 2, v[16:17]
	s_lshl_b32 s38, s8, 2
	v_lshl_add_u64 v[16:17], v[16:17], 0, s[38:39]
	global_store_dword v[16:17], v19, off
	global_store_dword v[16:17], v18, off offset:64

.LBB0_601:
	s_waitcnt lgkmcnt(0)
	v_pk_mul_f32 v[12:13], v[12:13], v[20:21] op_sel_hi:[1,0]
	v_lshlrev_b64 v[18:19], 12, v[16:17]
	v_mul_f32_e32 v21, v12, v12
	v_fmamk_f32 v21, v21, 0xbdd2d3e7, v152
	v_mul_f32_e32 v21, v12, v21
	v_exp_f32_e32 v21, v21
	v_mul_f32_e32 v23, v13, v13
	v_fmamk_f32 v23, v23, 0xbdd2d3e7, v152
	v_mul_f32_e32 v23, v13, v23
	v_pk_mul_f32 v[8:9], v[8:9], v[20:21] op_sel_hi:[1,0]
	v_pk_mul_f32 v[14:15], v[14:15], v[20:21] op_sel_hi:[1,0]
	v_mul_f32_e32 v24, v9, v9
	v_fmamk_f32 v24, v24, 0xbdd2d3e7, v152
	v_mul_f32_e32 v24, v9, v24
	v_pk_mul_f32 v[10:11], v[10:11], v[20:21] op_sel_hi:[1,0]
	v_exp_f32_e32 v24, v24
	v_mul_f32_e32 v26, v14, v14
	v_mul_f32_e32 v27, v10, v10
	v_fmamk_f32 v26, v26, 0xbdd2d3e7, v152
	v_fmamk_f32 v27, v27, 0xbdd2d3e7, v152
	v_mul_f32_e32 v22, v8, v8
	v_mul_f32_e32 v26, v14, v26
	v_mul_f32_e32 v27, v10, v27
	v_fmamk_f32 v22, v22, 0xbdd2d3e7, v152
	v_mul_f32_e32 v22, v8, v22
	v_add_f32_e32 v24, 1.0, v24
	v_rcp_f32_e32 v24, v24
	v_exp_f32_e32 v26, v26
	v_exp_f32_e32 v27, v27
	v_exp_f32_e32 v22, v22
	v_mul_f32_e32 v28, v11, v11
	v_exp_f32_e32 v23, v23
	v_mul_f32_e32 v24, v9, v24
	v_add_f32_e32 v9, 1.0, v26
	v_add_f32_e32 v26, 1.0, v27
	v_mul_f32_e32 v27, v15, v15
	v_fmamk_f32 v28, v28, 0xbdd2d3e7, v152
	v_fmamk_f32 v27, v27, 0xbdd2d3e7, v152
	v_mul_f32_e32 v28, v11, v28
	v_add_f32_e32 v22, 1.0, v22
	v_mul_f32_e32 v27, v15, v27
	v_add_f32_e32 v21, 1.0, v21
	v_rcp_f32_e32 v22, v22
	v_rcp_f32_e32 v21, v21
	v_add_f32_e32 v23, 1.0, v23
	v_exp_f32_e32 v28, v28
	v_rcp_f32_e32 v23, v23
	v_exp_f32_e32 v27, v27
	v_rcp_f32_e32 v26, v26
	v_mul_f32_e32 v22, v8, v22
	v_rcp_f32_e32 v9, v9
	v_mul_f32_e32 v25, v12, v21
	v_add_f32_e32 v28, 1.0, v28
	v_fma_f32 v12, v12, v21, v22
	v_mul_f32_e32 v8, v13, v23
	v_add_f32_e32 v27, 1.0, v27
	v_rcp_f32_e32 v28, v28
	v_add_f32_e32 v12, 0, v12
	v_mul_f32_e32 v21, v22, v22
	v_fma_f32 v13, v13, v23, v24
	v_rcp_f32_e32 v27, v27
	v_mul_f32_e32 v26, v10, v26
	v_fmac_f32_e32 v21, v25, v25
	v_add_f32_e32 v12, v13, v12
	v_mul_f32_e32 v13, v24, v24
	v_mul_f32_e32 v29, v14, v9
	v_fmac_f32_e32 v13, v8, v8
	v_fma_f32 v9, v14, v9, v26
	v_pk_mul_f32 v[0:1], v[0:1], v[20:21] op_sel_hi:[1,0]
	v_add_f32_e32 v13, v21, v13
	v_add_f32_e32 v9, v9, v12
	v_mul_f32_e32 v12, v26, v26
	v_pk_mul_f32 v[4:5], v[4:5], v[20:21] op_sel_hi:[1,0]
	v_pk_mul_f32 v[6:7], v[6:7], v[20:21] op_sel_hi:[1,0]
	v_pk_mul_f32 v[2:3], v[2:3], v[20:21] op_sel_hi:[1,0]
	v_mul_f32_e32 v21, v1, v1
	v_mul_f32_e32 v11, v11, v28
	v_fmac_f32_e32 v12, v29, v29
	v_fmamk_f32 v21, v21, 0xbdd2d3e7, v152
	v_add_f32_e32 v12, v12, v13
	v_fma_f32 v13, v15, v27, v11
	v_mul_f32_e32 v21, v1, v21
	v_mul_f32_e32 v10, v15, v27
	v_add_f32_e32 v13, v13, v9
	v_mul_f32_e32 v9, v11, v11
	v_fmac_f32_e32 v9, v10, v10
	v_add_f32_e32 v12, v9, v12
	v_cvt_pk_bf16_f32 v8, v25, v8
	v_cvt_pk_bf16_f32 v9, v29, v10
	v_cvt_pk_bf16_f32 v10, v22, v24
	v_exp_f32_e32 v21, v21
	v_mul_f32_e32 v23, v6, v6
	v_mul_f32_e32 v24, v2, v2
	v_fmamk_f32 v23, v23, 0xbdd2d3e7, v152
	v_fmamk_f32 v24, v24, 0xbdd2d3e7, v152
	v_mul_f32_e32 v23, v6, v23
	v_mul_f32_e32 v24, v2, v24
	v_mul_f32_e32 v15, v0, v0
	v_mul_f32_e32 v14, v4, v4
	v_fmamk_f32 v15, v15, 0xbdd2d3e7, v152
	v_add_f32_e32 v21, 1.0, v21
	v_fmamk_f32 v14, v14, 0xbdd2d3e7, v152
	v_mul_f32_e32 v15, v0, v15
	v_mul_f32_e32 v20, v5, v5
	v_rcp_f32_e32 v21, v21
	v_exp_f32_e32 v23, v23
	v_exp_f32_e32 v24, v24
	v_mul_f32_e32 v25, v3, v3
	v_mul_f32_e32 v14, v4, v14
	v_fmamk_f32 v20, v20, 0xbdd2d3e7, v152
	v_fmamk_f32 v25, v25, 0xbdd2d3e7, v152
	v_mul_f32_e32 v20, v5, v20
	v_mul_f32_e32 v25, v3, v25
	v_exp_f32_e32 v15, v15
	v_exp_f32_e32 v14, v14
	v_mul_f32_e32 v21, v1, v21
	v_add_f32_e32 v1, 1.0, v23
	v_add_f32_e32 v23, 1.0, v24
	v_mul_f32_e32 v24, v7, v7
	v_exp_f32_e32 v20, v20
	v_fmamk_f32 v24, v24, 0xbdd2d3e7, v152
	v_exp_f32_e32 v25, v25
	v_mul_f32_e32 v24, v7, v24
	v_add_f32_e32 v15, 1.0, v15
	v_add_f32_e32 v14, 1.0, v14
	v_rcp_f32_e32 v15, v15
	v_rcp_f32_e32 v14, v14
	v_add_f32_e32 v20, 1.0, v20
	v_exp_f32_e32 v24, v24
	v_rcp_f32_e32 v23, v23
	v_add_f32_e32 v25, 1.0, v25
	v_rcp_f32_e32 v20, v20
	v_rcp_f32_e32 v25, v25
	v_rcp_f32_e32 v1, v1
	v_mul_f32_e32 v15, v0, v15
	v_add_f32_e32 v24, 1.0, v24
	v_mul_f32_e32 v23, v2, v23
	v_fma_f32 v2, v4, v14, v15
	v_mul_f32_e32 v22, v4, v14
	v_rcp_f32_e32 v24, v24
	v_mul_f32_e32 v25, v3, v25
	v_add_f32_e32 v2, v2, v13
	v_mul_f32_e32 v3, v15, v15
	v_fma_f32 v4, v5, v20, v21
	v_cvt_pk_bf16_f32 v11, v26, v11
	v_mul_f32_e32 v0, v5, v20
	v_mul_f32_e32 v26, v6, v1
	v_fmac_f32_e32 v3, v22, v22
	v_add_f32_e32 v2, v4, v2
	v_mul_f32_e32 v4, v21, v21
	v_fma_f32 v1, v6, v1, v23
	v_add_f32_e32 v3, v3, v12
	v_fmac_f32_e32 v4, v0, v0
	v_add_f32_e32 v1, v1, v2
	v_mul_f32_e32 v2, v23, v23
	v_add_f32_e32 v3, v4, v3
	v_fmac_f32_e32 v2, v26, v26
	v_add_f32_e32 v2, v2, v3
	v_fma_f32 v3, v7, v24, v25
	v_mul_f32_e32 v27, v7, v24
	v_add_f32_e32 v1, v3, v1
	v_mul_f32_e32 v3, v25, v25
	v_fmac_f32_e32 v3, v27, v27
	v_add_f32_e32 v2, v3, v2
	ds_bpermute_b32 v5, v168, v1
	ds_bpermute_b32 v3, v168, v2
	v_lshl_add_u64 v[18:19], s[70:71], 0, v[18:19]
	v_lshl_add_u64 v[18:19], v[160:161], 1, v[18:19]
	global_store_dwordx4 v[18:19], v[8:11], off nt
	v_cvt_pk_bf16_f32 v4, v22, v0
	s_waitcnt lgkmcnt(0)
	v_add_f32_e32 v0, v1, v5
	v_add_f32_e32 v2, v2, v3
	ds_bpermute_b32 v1, v167, v0
	ds_bpermute_b32 v3, v167, v2
	v_cvt_pk_bf16_f32 v5, v26, v27
	v_cvt_pk_bf16_f32 v6, v15, v21
	v_cvt_pk_bf16_f32 v7, v23, v25
	global_store_dwordx4 v[18:19], v[4:7], off offset:256 nt
	s_and_saveexec_b64 s[6:7], s[58:59]
	s_cbranch_execz .LBB0_603
	s_waitcnt lgkmcnt(0)
	v_add_f32_e32 v2, v2, v3
	v_add_f32_e32 v3, v0, v1
	s_lshl_b32 s4, s95, 2
	v_lshlrev_b64 v[0:1], 7, v[16:17]
	s_add_i32 s38, s4, -16
	v_lshl_add_u64 v[0:1], s[72:73], 0, v[0:1]
	v_lshl_add_u64 v[0:1], s[38:39], 2, v[0:1]
	s_lshl_b32 s38, s8, 2
	v_lshl_add_u64 v[0:1], v[0:1], 0, s[38:39]
	global_store_dword v[0:1], v3, off
	global_store_dword v[0:1], v2, off offset:64
